# rstd LDS-sharing now in all three rows_rstd<32> epilogues (Swiglu, InOdd, InEven) + stick-breaking exact early exit; bit-identical outputs
# speedup vs baseline: 1.0010x; 1.0010x over previous
; #define GAS __attribute__((address_space(1)))
; template <int LD, int S0, int NS>
; __device__ __forceinline__ void rows_rstd(const float* st, int row0, int fq, float inv_n, float (&r)[2][4]) {
; #pragma unroll
;     for (int ai = 0; ai < 2; ++ai)
; #pragma unroll
;         for (int m = 0; m < 4; ++m) {
;             const GAS float* p = (const GAS float*)st + (size_t)(row0 + ai * 128 + m * 16) * LD + S0;
;             float s = 0.f;
;             if (NS == 32) { const f32x4 a = *(const GAS f32x4*)(p + fq * 8), b = *(const GAS f32x4*)(p + fq * 8 + 4); s = (a.x + a.y) + (a.z + a.w) + (b.x + b.y) + (b.z + b.w); }
;             else { if (fq * 4 < NS) { const f32x4 a = *(const GAS f32x4*)(p + fq * 4); s = (a.x + a.y) + (a.z + a.w); } }
;             s += __shfl_xor(s, 16); s += __shfl_xor(s, 32);
;             r[ai][m] = 1.0f / sqrtf(s * inv_n + EPS);
;         }
; }
;     __device__ __forceinline__ void operator()(const Acc& acc, const Unit& u, int wr, int wc, int fr, int fq) const {
;     ...
;         const int row0 = u.pm * 256 + wr * 64 + fr, pn = u.pn, colw = pn * 256 + wc * 32 + 8 * fq;
;         float rs[2][4]; rows_rstd<32, 0, 32>(ssq, row0, fq, 1.0f / D, rs);
;         if (pn < 6) {
.LBB0_550:
	s_lshl_b32 s4, s8, 8
	v_mov_b32_e32 v177, v165
	v_mov_b32_e32 v130, v153
	s_add_i32 s4, s4, s66
	v_cmp_lt_i32_e32 vcc, v212, v218
	v_readlane_b32 s5, v254, 63
	v_add_u32_e32 v184, s4, v130
	v_lshlrev_b32_e32 v192, 3, v177
	v_cndmask_b32_e32 v132, v207, v212, vcc
	v_cmp_lt_i32_e32 vcc, v213, v218
	v_ashrrev_i32_e32 v193, 31, v192
	v_lshlrev_b32_e32 v181, 2, v132
	v_cndmask_b32_e32 v132, v207, v213, vcc
	v_ashrrev_i32_e32 v185, 31, v184
	v_lshl_add_u64 v[130:131], v[192:193], 2, s[68:69]
	v_lshlrev_b32_e32 v189, 2, v132
	v_lshlrev_b64 v[132:133], 7, v[184:185]
	v_lshl_add_u64 v[136:137], v[130:131], 0, v[132:133]
	s_and_b32 s4, s5, 32
	s_lshl_b32 s4, s4, 7
	s_and_b32 vcc_lo, s5, 64
	s_lshl_b32 vcc_lo, vcc_lo, 8
	s_add_i32 s4, s4, vcc_lo
	v_mov_b32_e32 v226, s4
	v_mov_b32_e32 v227, 0
	v_lshl_add_u64 v[224:225], v[136:137], 0, v[226:227]
	global_load_dwordx4 v[132:135], v[224:225], off offset:16
	global_load_dwordx4 v[148:151], v[224:225], off
	global_load_dwordx4 v[228:231], v[224:225], off offset:2064
	global_load_dwordx4 v[232:235], v[224:225], off offset:2048
	s_lshl_b32 s4, s54, 8
	s_or_b32 s4, s4, s5
	v_add_u32_e32 v186, s4, v192
	v_add_u32_e32 v182, 16, v184
	v_ashrrev_i32_e32 v183, 31, v182
	v_add_u32_e32 v178, 32, v184
	v_ashrrev_i32_e32 v179, 31, v178
	v_add_u32_e32 v172, 48, v184
	s_waitcnt lgkmcnt(0)
	v_ashrrev_i32_e32 v173, 31, v172
	v_add_u32_e32 v168, 0x80, v184
	v_ashrrev_i32_e32 v169, 31, v168
	v_add_u32_e32 v166, 0x90, v184
	v_ashrrev_i32_e32 v167, 31, v166
	s_cmp_lt_i32 s54, 6
	v_ashrrev_i32_e32 v187, 31, v186
	s_waitcnt vmcnt(2)
	v_add_f32_e32 v132, v132, v133
	v_add_f32_e32 v136, v148, v149
	v_add_f32_e32 v137, v150, v151
	v_add_f32_e32 v136, v136, v137
	v_add_f32_e32 v132, v136, v132
	v_add_f32_e32 v133, v134, v135
	v_add_f32_e32 v132, v133, v132
	ds_bpermute_b32 v133, v181, v132
	s_waitcnt lgkmcnt(0)
	v_add_f32_e32 v132, v132, v133
	ds_bpermute_b32 v133, v189, v132
	s_waitcnt lgkmcnt(0)
	v_add_f32_e32 v132, v132, v133
	v_fmamk_f32 v132, v132, 0x3a000000, v205
	v_cmp_gt_f32_e32 vcc, s16, v132
	v_mul_f32_e32 v133, 0x4f800000, v132
	s_nop 0
	v_cndmask_b32_e32 v132, v132, v133, vcc
	v_sqrt_f32_e32 v133, v132
	s_nop 0
	v_add_u32_e32 v134, -1, v133
	v_fma_f32 v135, -v134, v133, v132
	v_cmp_ge_f32_e64 s[8:9], 0, v135
	v_add_u32_e32 v135, 1, v133
	s_nop 0
	v_cndmask_b32_e64 v134, v133, v134, s[8:9]
	v_fma_f32 v133, -v135, v133, v132
	v_cmp_lt_f32_e64 s[8:9], 0, v133
	s_nop 1
	v_cndmask_b32_e64 v133, v134, v135, s[8:9]
	v_mul_f32_e32 v134, 0x37800000, v133
	v_cndmask_b32_e32 v133, v133, v134, vcc
	v_cmp_class_f32_e32 vcc, v132, v206
	s_nop 1
	v_cndmask_b32_e32 v132, v133, v132, vcc
	v_div_scale_f32 v133, s[4:5], v132, v132, 1.0
	v_rcp_f32_e32 v134, v133
	s_nop 0
	v_fma_f32 v135, -v133, v134, 1.0
	v_fmac_f32_e32 v134, v135, v134
	v_div_scale_f32 v135, vcc, 1.0, v132, 1.0
	v_mul_f32_e32 v136, v135, v134
	v_fma_f32 v137, -v133, v136, v135
	v_fmac_f32_e32 v136, v137, v134
	v_fma_f32 v133, -v133, v136, v135
	v_div_fmas_f32 v133, v133, v134, v136
	v_div_fixup_f32 v236, v133, v132, 1.0
	s_waitcnt vmcnt(0)
	v_mov_b32_e32 v132, v228
	v_mov_b32_e32 v133, v229
	v_mov_b32_e32 v134, v230
	v_mov_b32_e32 v135, v231
	v_mov_b32_e32 v148, v232
	v_mov_b32_e32 v149, v233
	v_mov_b32_e32 v150, v234
	v_mov_b32_e32 v151, v235
	v_add_f32_e32 v132, v132, v133
	v_add_f32_e32 v136, v148, v149
	v_add_f32_e32 v137, v150, v151
	v_add_f32_e32 v136, v136, v137
	v_add_f32_e32 v132, v136, v132
	v_add_f32_e32 v133, v134, v135
	v_add_f32_e32 v132, v133, v132
	ds_bpermute_b32 v133, v181, v132
	s_waitcnt lgkmcnt(0)
	v_add_f32_e32 v132, v132, v133
	ds_bpermute_b32 v133, v189, v132
	s_waitcnt lgkmcnt(0)
	v_add_f32_e32 v132, v132, v133
	v_fmamk_f32 v132, v132, 0x3a000000, v205
	v_cmp_gt_f32_e32 vcc, s16, v132
	v_mul_f32_e32 v133, 0x4f800000, v132
	s_nop 0
	v_cndmask_b32_e32 v132, v132, v133, vcc
	v_sqrt_f32_e32 v133, v132
	s_nop 0
	v_add_u32_e32 v134, -1, v133
	v_fma_f32 v135, -v134, v133, v132
	v_cmp_ge_f32_e64 s[8:9], 0, v135
	v_add_u32_e32 v135, 1, v133
	s_nop 0
	v_cndmask_b32_e64 v134, v133, v134, s[8:9]
	v_fma_f32 v133, -v135, v133, v132
	v_cmp_lt_f32_e64 s[8:9], 0, v133
	s_nop 1
	v_cndmask_b32_e64 v133, v134, v135, s[8:9]
	v_mul_f32_e32 v134, 0x37800000, v133
	v_cndmask_b32_e32 v133, v133, v134, vcc
	v_cmp_class_f32_e32 vcc, v132, v206
	s_nop 1
	v_cndmask_b32_e32 v132, v133, v132, vcc
	v_div_scale_f32 v133, s[4:5], v132, v132, 1.0
	v_rcp_f32_e32 v134, v133
	s_nop 0
	v_fma_f32 v135, -v133, v134, 1.0
	v_fmac_f32_e32 v134, v135, v134
	v_div_scale_f32 v135, vcc, 1.0, v132, 1.0
	v_mul_f32_e32 v136, v135, v134
	v_fma_f32 v137, -v133, v136, v135
	v_fmac_f32_e32 v136, v137, v134
	v_fma_f32 v133, -v133, v136, v135
	v_div_fmas_f32 v133, v133, v134, v136
	v_div_fixup_f32 v237, v133, v132, 1.0
	v_readlane_b32 s5, v254, 63
	s_lshl_b32 s4, s66, 3
	s_lshl_b32 s5, s5, 2
	s_add_i32 s4, s4, 139392
	s_add_i32 s5, s5, s4
	v_lshl_add_u32 v238, v153, 2, s5
	v_lshl_add_u32 v239, v153, 2, s4
	ds_write_b32 v238, v236
	ds_write_b32 v238, v237 offset:64
	s_waitcnt lgkmcnt(0)
	s_barrier
	ds_read_b32 v190, v239
	ds_read_b32 v188, v239 offset:64
	ds_read_b32 v180, v239 offset:128
	ds_read_b32 v176, v239 offset:192
	ds_read_b32 v174, v239 offset:256
	ds_read_b32 v170, v239 offset:320
	ds_read_b32 v152, v239 offset:384
	ds_read_b32 v134, v239 offset:448
	v_add_u32_e32 v150, 0xa0, v184
	v_ashrrev_i32_e32 v151, 31, v150
	v_add_u32_e32 v148, 0xb0, v184
	v_ashrrev_i32_e32 v149, 31, v148
	s_mov_b64 s[4:5], -1
	s_waitcnt lgkmcnt(0)
	s_cmp_lt_i32 s54, 6
	s_cbranch_scc0 .LBB0_553
	s_and_b64 vcc, exec, s[4:5]
	s_cbranch_vccnz .LBB0_658
